# layer-0 w_in post pass: one-unit workgroups take over unit 0 of a same-XCC two-unit workgroup after their transposes (second round through the post set-up)
# baseline (speedup 1.0000x reference)
.Lxb1_rel:
.Lxb1_done:
.LBB0_220:
	s_or_b64 exec, exec, s[4:5]
	s_waitcnt lgkmcnt(0)
	s_barrier
	s_mov_b32 s99, 0
	s_load_dwordx2 s[8:9], s[82:83], 0xb0
	s_lshl_b32 s0, s64, 5
	s_lshr_b32 s63, s68, 8
	s_and_b32 s55, s0, 0x60
	s_mov_b32 s54, 0
	s_mov_b32 s1, 0
	s_cmpk_lt_i32 s93, 0x154
	s_cbranch_scc1 .LBB0_222
	s_ashr_i32 s57, s74, 31
	s_mov_b32 s56, s74
	s_mov_b64 s[4:5], 0
	s_branch .LBB0_223

.LBB0_247:
	s_mov_b32 s0, 0
	s_load_dwordx2 s[14:15], s[82:83], 0xa8
	v_mbcnt_lo_u32_b32 v0, -1, s0
	v_mbcnt_hi_u32_b32 v1, -1, v0
	v_lshlrev_b32_e32 v2, 4, v1
	v_and_b32_e32 v98, 16, v2
	v_and_b32_e32 v2, 2, v1
	s_waitcnt vmcnt(0)
	v_add_u32_e32 v12, s72, v1
	v_cmp_eq_u32_e64 s[6:7], 0, v2
	v_lshlrev_b32_e32 v2, 5, v1
	v_and_b32_e32 v4, 0xc0, v2
	v_and_b32_e32 v5, 32, v2
	v_bfe_u32 v16, v12, 6, 1
	v_and_b32_e32 v2, 31, v1
	v_and_b32_e32 v13, 7, v1
	v_bfe_u32 v15, v12, 7, 1
	v_lshl_or_b32 v2, v16, 5, v2
	s_movk_i32 s0, 0x210
	v_lshrrev_b32_e32 v1, 2, v1
	v_ashrrev_i32_e32 v100, 3, v12
	v_add_u32_e32 v17, 0x200, v12
	v_mad_u32_u24 v2, v2, s0, 0
	v_lshlrev_b32_e32 v3, 5, v15
	v_and_b32_e32 v1, 8, v1
	v_ashrrev_i32_e32 v101, 3, v17
	v_add_u32_e32 v18, 0x400, v12
	v_and_b32_e32 v6, 31, v100
	v_add3_u32 v1, v2, v3, v1
	v_lshlrev_b32_e32 v2, 4, v12
	v_ashrrev_i32_e32 v102, 3, v18
	v_add_u32_e32 v19, 0x600, v12
	v_or3_b32 v20, v6, v4, v5
	v_and_b32_e32 v6, 31, v101
	v_mov_b32_e32 v25, 0
	v_and_b32_e32 v24, 0x3f0, v2
	v_ashrrev_i32_e32 v103, 3, v19
	v_or3_b32 v21, v4, v6, v5
	v_and_b32_e32 v6, 31, v102
	v_lshlrev_b32_e32 v16, 10, v16
	s_waitcnt lgkmcnt(0)
	v_lshl_add_u64 v[2:3], s[14:15], 0, v[24:25]
	v_or3_b32 v22, v4, v6, v5
	v_and_b32_e32 v6, 31, v103
	v_lshl_or_b32 v24, v15, 11, v16
	v_or3_b32 v23, v4, v6, v5
	v_ashrrev_i32_e32 v4, 5, v12
	v_ashrrev_i32_e32 v6, 5, v17
	v_ashrrev_i32_e32 v8, 5, v18
	v_ashrrev_i32_e32 v10, 5, v19
	v_lshl_add_u64 v[26:27], v[2:3], 0, v[24:25]
	v_and_b32_e32 v2, 7, v12
	v_and_b32_e32 v4, -8, v4
	v_and_b32_e32 v6, -8, v6
	v_and_b32_e32 v8, -8, v8
	v_and_b32_e32 v10, -8, v10
	v_lshlrev_b32_e32 v24, 4, v2
	v_mul_lo_u32 v48, v4, s0
	v_mul_lo_u32 v49, v6, s0
	v_mul_lo_u32 v50, v8, s0
	v_mul_lo_u32 v51, v10, s0
	v_lshl_add_u64 v[2:3], s[8:9], 0, v[24:25]
	s_mov_b64 s[0:1], 0x9600000
	v_lshlrev_b32_e32 v24, 4, v13
	v_ashrrev_i32_e32 v5, 31, v4
	v_lshl_add_u64 v[36:37], v[2:3], 0, s[0:1]
	v_lshl_add_u64 v[2:3], s[8:9], 0, v[24:25]
	v_ashrrev_i32_e32 v7, 31, v6
	v_lshl_add_u64 v[38:39], v[2:3], 0, s[0:1]
	v_lshl_add_u64 v[2:3], v[4:5], 1, s[8:9]
	v_ashrrev_i32_e32 v9, 31, v8
	v_lshl_add_u64 v[40:41], v[2:3], 0, s[0:1]
	v_lshl_add_u64 v[2:3], v[6:7], 1, s[8:9]
	v_lshlrev_b32_e32 v0, 3, v12
	v_and_b32_e32 v99, 0xff, v12
	v_ashrrev_i32_e32 v11, 31, v10
	v_ashrrev_i32_e32 v104, 8, v12
	v_ashrrev_i32_e32 v105, 8, v17
	v_ashrrev_i32_e32 v106, 8, v18
	v_ashrrev_i32_e32 v107, 8, v19
	v_lshl_add_u64 v[42:43], v[2:3], 0, s[0:1]
	v_lshl_add_u64 v[2:3], v[8:9], 1, s[8:9]
	s_add_u32 s16, s8, 0x50000
	v_and_b32_e32 v0, 56, v0
	v_lshl_add_u32 v14, v99, 1, 0
	v_lshlrev_b32_e32 v52, 6, v104
	v_lshlrev_b32_e32 v15, 6, v105
	v_lshlrev_b32_e32 v16, 6, v106
	v_lshlrev_b32_e32 v17, 6, v107
	v_lshl_add_u64 v[44:45], v[2:3], 0, s[0:1]
	v_lshl_add_u64 v[2:3], v[10:11], 1, s[8:9]
	s_mov_b32 s13, 0
	s_addc_u32 s17, s9, 0
	v_cmp_lt_u32_e64 s[4:5], 3, v13
	v_lshlrev_b32_e32 v28, 4, v20
	v_mov_b32_e32 v29, v25
	v_lshlrev_b32_e32 v30, 4, v21
	v_mov_b32_e32 v31, v25
	v_lshlrev_b32_e32 v32, 4, v22
	v_mov_b32_e32 v33, v25
	v_lshlrev_b32_e32 v34, 4, v23
	v_mov_b32_e32 v35, v25
	v_lshl_add_u64 v[46:47], v[2:3], 0, s[0:1]
	s_mov_b32 s0, 0x880000
	s_movk_i32 s1, 0x7e0
	s_movk_i32 s2, 0xa00
	v_lshlrev_b32_e32 v108, 2, v0
	v_mov_b32_e32 v109, 0x358637bd
	v_add_u32_e32 v110, v14, v48
	v_add_u32_e32 v111, v14, v49
	v_add_u32_e32 v112, v14, v50
	v_add_u32_e32 v113, v14, v51
	v_add_u32_e32 v114, v1, v52
	v_add_u32_e32 v115, v1, v15
	v_add_u32_e32 v116, v1, v16
	v_add_u32_e32 v117, v1, v17
	v_mov_b64_e32 v[48:49], 0x153
	v_mov_b64_e32 v[50:51], 0x154
	v_mov_b32_e32 v118, 0x3e38aa3b
	s_mov_b32 s30, 0
	s_cmp_eq_u32 s99, 1
	s_cbranch_scc1 .Lq2_second
	s_cmp_lg_u32 s56, 0x100
	s_cbranch_scc1 .Lq2_generic
	s_cmp_lg_u32 s57, 0
	s_cbranch_scc1 .Lq2_generic
	s_mov_b32 s94, s93
.Lq2_second:
	s_mov_b32 s95, -1
	s_getreg_b32 s96, hwreg(HW_REG_XCC_ID, 0, 4)
	s_and_b32 s96, s96, 15
	s_load_dwordx2 s[40:41], s[82:83], 0xb0
	s_mov_b64 s[44:45], 0
	s_and_b64 vcc, exec, s[58:59]
	s_cbranch_vccnz .Lq2_nolead
	v_mbcnt_lo_u32_b32 v150, -1, 0
	v_mbcnt_hi_u32_b32 v150, -1, v150
	v_cmp_eq_u32_e32 vcc, 0, v150
	s_and_b64 s[44:45], vcc, exec
.Lq2_nolead:
	s_waitcnt lgkmcnt(0)
	s_add_u32 s40, s40, 0x3800
	s_addc_u32 s41, s41, 0
	s_cmp_lt_u32 s94, 0x54
	s_cselect_b32 s97, 1, 0
	s_waitcnt vmcnt(0)
	s_barrier
	s_cmp_eq_u32 s97, 0
	s_cbranch_scc1 .Lq2_next
	s_and_saveexec_b64 s[42:43], s[44:45]
	s_cbranch_execz .Lq2_pub_done
	s_add_u32 s46, s96, 1
	s_lshl_b32 s47, s94, 2
	v_mov_b32_e32 v150, s47
	v_mov_b32_e32 v151, s46
	global_atomic_or v150, v151, s[40:41]

.Lq2_next:
	s_add_i32 s95, s95, 1
	s_cmp_eq_u32 s97, 0
	s_cbranch_scc1 .Lq2_light
	s_cmp_gt_u32 s95, 1
	s_cbranch_scc1 .Lq2_exit
	s_mov_b32 s48, s94
	s_mov_b32 s49, 1
	s_mov_b32 s50, 0
	s_cmp_eq_u32 s95, 0
	s_cbranch_scc1 .Lq2_run
	s_mov_b32 s49, 0
	s_branch .Lq2_claim
.Lq2_light:
	s_cmp_gt_u32 s95, 0
	s_cbranch_scc1 .Lq2_exit
	s_mov_b32 s48, s94
	s_mov_b32 s49, 0
	s_cmp_eq_u32 s99, 1
	s_cbranch_scc0 .Lq2_run
	s_mov_b32 s48, s98
	s_mov_b32 s50, 1
.Lq2_claim:
	s_mov_b32 s51, 0
	s_and_saveexec_b64 s[42:43], s[44:45]
	s_cbranch_execz .Lq2_cl_done
	s_lshl_b32 s46, s48, 2
	v_mov_b32_e32 v150, s46
	s_cmp_eq_u32 s50, 0
	s_cbranch_scc1 .Lq2_cl_try
	s_mov_b32 s47, 0
.Lq2_cl_poll:
	global_load_dword v152, v150, s[40:41] sc1
	s_waitcnt vmcnt(0)
	v_readfirstlane_b32 s52, v152
	s_and_b32 s53, s52, 31
	s_cmp_lg_u32 s53, 0
	s_cbranch_scc1 .Lq2_cl_ready
	s_add_u32 s47, s47, 1
	s_cmp_lt_u32 s47, 100
	s_cbranch_scc0 .Lq2_cl_write
	s_sleep 8
	s_branch .Lq2_cl_poll
.Lq2_cl_ready:
	s_add_i32 s53, s53, -1
	s_cmp_lg_u32 s53, s96
	s_cbranch_scc1 .Lq2_cl_write
.Lq2_cl_try:
	v_mov_b32_e32 v151, 0x100
	global_atomic_or v152, v150, v151, s[40:41] sc0
	s_waitcnt vmcnt(0)
	v_readfirstlane_b32 s52, v152
	s_and_b32 s52, s52, 0x100
	s_cmp_eq_u32 s52, 0
	s_cselect_b32 s51, 1, 0
	buffer_inv sc1
	s_waitcnt vmcnt(0)
.Lq2_cl_write:
	v_mov_b32_e32 v151, s51
	v_mov_b32_e32 v153, 0x25014
	ds_write_b32 v153, v151
	s_waitcnt lgkmcnt(0)
.Lq2_cl_done:
	s_or_b64 exec, exec, s[42:43]
	s_barrier
	v_mov_b32_e32 v153, 0x25014
	ds_read_b32 v151, v153
	s_waitcnt lgkmcnt(0)
	v_readfirstlane_b32 s51, v151
	s_barrier
	s_cmp_eq_u32 s51, 0
	s_cbranch_scc1 .Lq2_next
.Lq2_run:
	s_mov_b32 s93, s48
	s_mov_b32 s30, s49
	s_branch .LBB0_250
.Lq2_exit:
	s_mov_b32 s93, s94
	s_branch .LBB0_288
.Lq2_generic:
	s_mov_b32 s99, 3
	s_branch .LBB0_250
.LBB0_248:
	s_cmp_eq_u32 s99, 3
	s_cbranch_scc0 .Lq2_next
	s_add_i32 s30, s30, 1
	s_mov_b64 s[8:9], 0

.LBB0_288:
	s_cmp_eq_u32 s99, 1
	s_cbranch_scc0 .Lq2_first_exit
	s_mov_b32 s99, 2
	s_mov_b32 s30, 0
	s_waitcnt lgkmcnt(0)
	s_barrier
	s_branch .LBB0_384

.LBB0_384:
	s_cmp_lg_u32 s99, 0
	s_cbranch_scc1 .Lq2_hook_done
	s_cmp_lt_u32 s93, 0x54
	s_cbranch_scc1 .Lq2_hook_done
	s_and_b32 s46, s93, 7
	s_lshr_b32 s47, s93, 3
	s_cmp_lt_u32 s46, 4
	s_cselect_b32 s48, 11, 10
	s_sub_u32 s47, s47, s48
	s_lshl3_add_u32 s98, s47, s46
	s_cmp_gt_u32 s98, 0x53
	s_cbranch_scc1 .Lq2_hook_done
	s_mov_b32 s99, 1
	s_load_dwordx2 s[8:9], s[82:83], 0xb0
	s_branch .LBB0_247
